# combo3 + NSA part-B: unmasked fast paths for fully-valid window sub-tiles and below-diagonal selected sub-tiles (bit-identical outputs)
# speedup vs baseline: 1.0071x; 1.0071x over previous
.LBB0_709:
	v_lshrrev_b32_e32 v32, s33, v59
	v_and_b32_e32 v32, 1, v32
	s_lshl_b32 s6, s33, 6
	v_add_u32_e32 v79, s44, v120
	v_cmp_eq_u32_e64 s[44:45], 1, v32
	v_add_u32_e32 v77, v79, v141
	s_cmp_gt_i32 s6, s17
	v_cndmask_b32_e64 v96, 0, 1, s[44:45]
	s_cbranch_scc1 .LBB0_714
	v_cmp_ne_u32_e32 vcc, 0, v96
	s_cbranch_vccz .LBB0_714
	v_add_u32_e32 v36, v79, v123
	ds_read_b128 v[32:35], v36
	ds_read_b128 v[98:101], v36 offset:32
	ds_read_b128 v[146:149], v36 offset:64
	ds_read_b128 v[150:153], v36 offset:96
	s_setprio 1
	s_waitcnt lgkmcnt(0)
	v_mfma_f32_32x32x16_bf16 v[32:47], v[32:35], v[80:83], 0
	v_mfma_f32_32x32x16_bf16 v[32:47], v[98:101], v[84:87], v[32:47]
	v_mfma_f32_32x32x16_bf16 v[32:47], v[146:149], v[88:91], v[32:47]
	v_mfma_f32_32x32x16_bf16 v[32:47], v[150:153], v[92:95], v[32:47]
	s_setprio 0
	s_sub_i32 m0, s17, 62
	s_cmp_le_i32 s6, m0
	s_cbranch_scc0 .Lsel0_masked
	v_cndmask_b32_e64 v166, v212, 0, s[44:45]
	s_nop 7
	v_fma_f32 v119, v32, s28, v166
	v_fma_f32 v118, v33, s28, v166
	v_fma_f32 v103, v34, s28, v166
	v_fma_f32 v102, v35, s28, v166
	v_fma_f32 v101, v36, s28, v166
	v_fma_f32 v100, v37, s28, v166
	v_fma_f32 v99, v38, s28, v166
	v_fma_f32 v98, v39, s28, v166
	v_fma_f32 v97, v40, s28, v166
	v_fma_f32 v40, v41, s28, v166
	v_fma_f32 v39, v42, s28, v166
	v_fma_f32 v38, v43, s28, v166
	v_fma_f32 v37, v44, s28, v166
	v_fma_f32 v36, v45, s28, v166
	v_fma_f32 v35, v46, s28, v166
	v_fma_f32 v34, v47, s28, v166
	v_max_f32_e32 v43, v35, v34
	v_max_f32_e32 v32, v103, v102
	v_max_f32_e32 v33, v99, v98
	v_max_f32_e32 v41, v97, v40
	v_max_f32_e32 v42, v39, v38
	v_max3_f32 v43, v37, v36, v43
	v_max3_f32 v32, v119, v118, v32
	v_max3_f32 v33, v101, v100, v33
	v_max3_f32 v41, v41, v42, v43
	v_max3_f32 v32, v32, v33, v41
	s_branch .Lsel0_join
.Lsel0_masked:
	v_or_b32_e32 v97, s6, v110
	v_sub_u32_e32 v97, v58, v97
	v_cmp_lt_i32_e32 vcc, -1, v97
	s_nop 7
	v_mul_f32_e32 v32, 0x3e38aa3b, v32
	s_and_b64 vcc, s[44:45], vcc
	v_cndmask_b32_e32 v119, v212, v32, vcc
	v_add_u32_e32 v32, s6, v113
	v_cmp_gt_i32_e32 vcc, 0, v32
	v_mul_f32_e32 v32, 0x3e38aa3b, v33
	s_and_b64 vcc, s[44:45], vcc
	v_cndmask_b32_e32 v118, v212, v32, vcc
	v_subrev_u32_e32 v32, s6, v63
	v_cmp_lt_i32_e32 vcc, -1, v32
	v_mul_f32_e32 v32, 0x3e38aa3b, v34
	s_and_b64 vcc, s[44:45], vcc
	v_cndmask_b32_e32 v103, v212, v32, vcc
	v_subrev_u32_e32 v32, s6, v64
	v_cmp_lt_i32_e32 vcc, -1, v32
	v_mul_f32_e32 v32, 0x3e38aa3b, v35
	s_and_b64 vcc, s[44:45], vcc
	v_cndmask_b32_e32 v102, v212, v32, vcc
	v_subrev_u32_e32 v32, s6, v65
	v_cmp_lt_i32_e32 vcc, -1, v32
	v_mul_f32_e32 v32, 0x3e38aa3b, v36
	s_and_b64 vcc, s[44:45], vcc
	v_cndmask_b32_e32 v101, v212, v32, vcc
	v_subrev_u32_e32 v32, s6, v66
	v_cmp_lt_i32_e32 vcc, -1, v32
	v_mul_f32_e32 v32, 0x3e38aa3b, v37
	s_and_b64 vcc, s[44:45], vcc
	v_cndmask_b32_e32 v100, v212, v32, vcc
	v_subrev_u32_e32 v32, s6, v67
	v_cmp_lt_i32_e32 vcc, -1, v32
	v_mul_f32_e32 v32, 0x3e38aa3b, v38
	s_and_b64 vcc, s[44:45], vcc
	v_cndmask_b32_e32 v99, v212, v32, vcc
	v_subrev_u32_e32 v32, s6, v68
	v_cmp_lt_i32_e32 vcc, -1, v32
	v_mul_f32_e32 v32, 0x3e38aa3b, v39
	s_and_b64 vcc, s[44:45], vcc
	v_cndmask_b32_e32 v98, v212, v32, vcc
	v_subrev_u32_e32 v32, s6, v69
	v_cmp_lt_i32_e32 vcc, -1, v32
	v_mul_f32_e32 v32, 0x3e38aa3b, v40
	s_and_b64 vcc, s[44:45], vcc
	v_cndmask_b32_e32 v97, v212, v32, vcc
	v_subrev_u32_e32 v32, s6, v70
	v_cmp_lt_i32_e32 vcc, -1, v32
	v_mul_f32_e32 v32, 0x3e38aa3b, v41
	s_and_b64 vcc, s[44:45], vcc
	v_cndmask_b32_e32 v40, v212, v32, vcc
	v_subrev_u32_e32 v32, s6, v71
	v_cmp_lt_i32_e32 vcc, -1, v32
	v_mul_f32_e32 v32, 0x3e38aa3b, v42
	s_and_b64 vcc, s[44:45], vcc
	v_cndmask_b32_e32 v39, v212, v32, vcc
	v_subrev_u32_e32 v32, s6, v72
	v_cmp_lt_i32_e32 vcc, -1, v32
	v_mul_f32_e32 v32, 0x3e38aa3b, v43
	s_and_b64 vcc, s[44:45], vcc
	v_cndmask_b32_e32 v38, v212, v32, vcc
	v_subrev_u32_e32 v32, s6, v73
	v_cmp_lt_i32_e32 vcc, -1, v32
	v_mul_f32_e32 v32, 0x3e38aa3b, v44
	s_and_b64 vcc, s[44:45], vcc
	v_cndmask_b32_e32 v37, v212, v32, vcc
	v_subrev_u32_e32 v32, s6, v74
	v_cmp_lt_i32_e32 vcc, -1, v32
	v_mul_f32_e32 v32, 0x3e38aa3b, v45
	s_and_b64 vcc, s[44:45], vcc
	v_cndmask_b32_e32 v36, v212, v32, vcc
	v_subrev_u32_e32 v32, s6, v75
	v_cmp_lt_i32_e32 vcc, -1, v32
	v_mul_f32_e32 v32, 0x3e38aa3b, v46
	s_and_b64 vcc, s[44:45], vcc
	v_cndmask_b32_e32 v35, v212, v32, vcc
	v_subrev_u32_e32 v32, s6, v76
	v_cmp_lt_i32_e32 vcc, -1, v32
	v_mul_f32_e32 v32, 0x3e38aa3b, v47
	s_and_b64 vcc, s[44:45], vcc
	v_cndmask_b32_e32 v34, v212, v32, vcc
	v_max_f32_e32 v43, v35, v34
	v_max_f32_e32 v32, v103, v102
	v_max_f32_e32 v33, v99, v98
	v_max_f32_e32 v41, v97, v40
	v_max_f32_e32 v42, v39, v38
	v_max3_f32 v43, v37, v36, v43
	v_max3_f32 v32, v119, v118, v32
	v_max3_f32 v33, v101, v100, v33
	v_max3_f32 v41, v41, v42, v43
	v_max3_f32 v32, v32, v33, v41
.Lsel0_join:
	ds_bpermute_b32 v33, v121, v32
	s_waitcnt lgkmcnt(0)
	v_max3_f32 v33, v78, v32, v33
	v_cmp_neq_f32_e32 vcc, s29, v33
	s_nop 1
	v_cndmask_b32_e32 v41, 0, v33, vcc
	v_sub_f32_e32 v32, v78, v41
	v_exp_f32_e32 v32, v32
	s_nop 0
	v_cmp_eq_f32_e32 vcc, 1.0, v32
	s_cmp_eq_u64 vcc, exec
	s_cbranch_scc1 .LBB0_713
	v_pk_mul_f32 v[14:15], v[14:15], v[32:33] op_sel_hi:[1,0]
	v_pk_mul_f32 v[12:13], v[12:13], v[32:33] op_sel_hi:[1,0]
	v_pk_mul_f32 v[10:11], v[10:11], v[32:33] op_sel_hi:[1,0]
	v_pk_mul_f32 v[8:9], v[8:9], v[32:33] op_sel_hi:[1,0]
	v_pk_mul_f32 v[6:7], v[6:7], v[32:33] op_sel_hi:[1,0]
	v_pk_mul_f32 v[4:5], v[4:5], v[32:33] op_sel_hi:[1,0]
	v_pk_mul_f32 v[2:3], v[2:3], v[32:33] op_sel_hi:[1,0]
	v_pk_mul_f32 v[0:1], v[0:1], v[32:33] op_sel_hi:[1,0]
	v_pk_mul_f32 v[30:31], v[30:31], v[32:33] op_sel_hi:[1,0]
	v_pk_mul_f32 v[28:29], v[28:29], v[32:33] op_sel_hi:[1,0]
	v_pk_mul_f32 v[26:27], v[26:27], v[32:33] op_sel_hi:[1,0]
	v_pk_mul_f32 v[24:25], v[24:25], v[32:33] op_sel_hi:[1,0]
	v_pk_mul_f32 v[22:23], v[22:23], v[32:33] op_sel_hi:[1,0]
	v_pk_mul_f32 v[20:21], v[20:21], v[32:33] op_sel_hi:[1,0]
	v_pk_mul_f32 v[18:19], v[18:19], v[32:33] op_sel_hi:[1,0]
	v_pk_mul_f32 v[16:17], v[16:17], v[32:33] op_sel_hi:[1,0]

.LBB0_714:
	s_or_b32 s6, s6, 32
	s_cmp_gt_i32 s6, s17
	s_cbranch_scc1 .LBB0_719
	v_cmp_ne_u32_e32 vcc, 0, v96
	s_cbranch_vccz .LBB0_719
	v_add_u32_e32 v36, v79, v123
	ds_read_b128 v[32:35], v36 offset:4608
	ds_read_b128 v[96:99], v36 offset:4640
	ds_read_b128 v[100:103], v36 offset:4672
	ds_read_b128 v[146:149], v36 offset:4704
	s_setprio 1
	s_waitcnt lgkmcnt(0)
	v_mfma_f32_32x32x16_bf16 v[32:47], v[32:35], v[80:83], 0
	v_mfma_f32_32x32x16_bf16 v[32:47], v[96:99], v[84:87], v[32:47]
	v_mfma_f32_32x32x16_bf16 v[32:47], v[100:103], v[88:91], v[32:47]
	v_mfma_f32_32x32x16_bf16 v[32:47], v[146:149], v[92:95], v[32:47]
	s_setprio 0
	s_sub_i32 m0, s17, 62
	s_cmp_le_i32 s6, m0
	s_cbranch_scc0 .Lsel1_masked
	v_cndmask_b32_e64 v166, v212, 0, s[44:45]
	s_nop 7
	v_fma_f32 v103, v32, s28, v166
	v_fma_f32 v102, v33, s28, v166
	v_fma_f32 v101, v34, s28, v166
	v_fma_f32 v100, v35, s28, v166
	v_fma_f32 v99, v36, s28, v166
	v_fma_f32 v98, v37, s28, v166
	v_fma_f32 v97, v38, s28, v166
	v_fma_f32 v96, v39, s28, v166
	v_fma_f32 v79, v40, s28, v166
	v_fma_f32 v40, v41, s28, v166
	v_fma_f32 v39, v42, s28, v166
	v_fma_f32 v38, v43, s28, v166
	v_fma_f32 v37, v44, s28, v166
	v_fma_f32 v36, v45, s28, v166
	v_fma_f32 v35, v46, s28, v166
	v_fma_f32 v34, v47, s28, v166
	v_max_f32_e32 v43, v35, v34
	v_max_f32_e32 v32, v101, v100
	v_max_f32_e32 v33, v97, v96
	v_max_f32_e32 v41, v79, v40
	v_max_f32_e32 v42, v39, v38
	v_max3_f32 v43, v37, v36, v43
	v_max3_f32 v32, v103, v102, v32
	v_max3_f32 v33, v99, v98, v33
	v_max3_f32 v41, v41, v42, v43
	v_max3_f32 v32, v32, v33, v41
	s_branch .Lsel1_join
.Lsel1_masked:
	v_or_b32_e32 v79, s6, v110
	v_sub_u32_e32 v79, v58, v79
	v_cmp_lt_i32_e32 vcc, -1, v79
	s_nop 7
	v_mul_f32_e32 v32, 0x3e38aa3b, v32
	s_and_b64 vcc, s[44:45], vcc
	v_cndmask_b32_e32 v103, v212, v32, vcc
	v_add_u32_e32 v32, s6, v113
	v_cmp_gt_i32_e32 vcc, 0, v32
	v_mul_f32_e32 v32, 0x3e38aa3b, v33
	s_and_b64 vcc, s[44:45], vcc
	v_cndmask_b32_e32 v102, v212, v32, vcc
	v_subrev_u32_e32 v32, s6, v63
	v_cmp_lt_i32_e32 vcc, -1, v32
	v_mul_f32_e32 v32, 0x3e38aa3b, v34
	s_and_b64 vcc, s[44:45], vcc
	v_cndmask_b32_e32 v101, v212, v32, vcc
	v_subrev_u32_e32 v32, s6, v64
	v_cmp_lt_i32_e32 vcc, -1, v32
	v_mul_f32_e32 v32, 0x3e38aa3b, v35
	s_and_b64 vcc, s[44:45], vcc
	v_cndmask_b32_e32 v100, v212, v32, vcc
	v_subrev_u32_e32 v32, s6, v65
	v_cmp_lt_i32_e32 vcc, -1, v32
	v_mul_f32_e32 v32, 0x3e38aa3b, v36
	s_and_b64 vcc, s[44:45], vcc
	v_cndmask_b32_e32 v99, v212, v32, vcc
	v_subrev_u32_e32 v32, s6, v66
	v_cmp_lt_i32_e32 vcc, -1, v32
	v_mul_f32_e32 v32, 0x3e38aa3b, v37
	s_and_b64 vcc, s[44:45], vcc
	v_cndmask_b32_e32 v98, v212, v32, vcc
	v_subrev_u32_e32 v32, s6, v67
	v_cmp_lt_i32_e32 vcc, -1, v32
	v_mul_f32_e32 v32, 0x3e38aa3b, v38
	s_and_b64 vcc, s[44:45], vcc
	v_cndmask_b32_e32 v97, v212, v32, vcc
	v_subrev_u32_e32 v32, s6, v68
	v_cmp_lt_i32_e32 vcc, -1, v32
	v_mul_f32_e32 v32, 0x3e38aa3b, v39
	s_and_b64 vcc, s[44:45], vcc
	v_cndmask_b32_e32 v96, v212, v32, vcc
	v_subrev_u32_e32 v32, s6, v69
	v_cmp_lt_i32_e32 vcc, -1, v32
	v_mul_f32_e32 v32, 0x3e38aa3b, v40
	s_and_b64 vcc, s[44:45], vcc
	v_cndmask_b32_e32 v79, v212, v32, vcc
	v_subrev_u32_e32 v32, s6, v70
	v_cmp_lt_i32_e32 vcc, -1, v32
	v_mul_f32_e32 v32, 0x3e38aa3b, v41
	s_and_b64 vcc, s[44:45], vcc
	v_cndmask_b32_e32 v40, v212, v32, vcc
	v_subrev_u32_e32 v32, s6, v71
	v_cmp_lt_i32_e32 vcc, -1, v32
	v_mul_f32_e32 v32, 0x3e38aa3b, v42
	s_and_b64 vcc, s[44:45], vcc
	v_cndmask_b32_e32 v39, v212, v32, vcc
	v_subrev_u32_e32 v32, s6, v72
	v_cmp_lt_i32_e32 vcc, -1, v32
	v_mul_f32_e32 v32, 0x3e38aa3b, v43
	s_and_b64 vcc, s[44:45], vcc
	v_cndmask_b32_e32 v38, v212, v32, vcc
	v_subrev_u32_e32 v32, s6, v73
	v_cmp_lt_i32_e32 vcc, -1, v32
	v_mul_f32_e32 v32, 0x3e38aa3b, v44
	s_and_b64 vcc, s[44:45], vcc
	v_cndmask_b32_e32 v37, v212, v32, vcc
	v_subrev_u32_e32 v32, s6, v74
	v_cmp_lt_i32_e32 vcc, -1, v32
	v_mul_f32_e32 v32, 0x3e38aa3b, v45
	s_and_b64 vcc, s[44:45], vcc
	v_cndmask_b32_e32 v36, v212, v32, vcc
	v_subrev_u32_e32 v32, s6, v75
	v_cmp_lt_i32_e32 vcc, -1, v32
	v_mul_f32_e32 v32, 0x3e38aa3b, v46
	s_and_b64 vcc, s[44:45], vcc
	v_cndmask_b32_e32 v35, v212, v32, vcc
	v_subrev_u32_e32 v32, s6, v76
	v_cmp_lt_i32_e32 vcc, -1, v32
	v_mul_f32_e32 v32, 0x3e38aa3b, v47
	s_and_b64 vcc, s[44:45], vcc
	v_cndmask_b32_e32 v34, v212, v32, vcc
	v_max_f32_e32 v43, v35, v34
	v_max_f32_e32 v32, v101, v100
	v_max_f32_e32 v33, v97, v96
	v_max_f32_e32 v41, v79, v40
	v_max_f32_e32 v42, v39, v38
	v_max3_f32 v43, v37, v36, v43
	v_max3_f32 v32, v103, v102, v32
	v_max3_f32 v33, v99, v98, v33
	v_max3_f32 v41, v41, v42, v43
	v_max3_f32 v32, v32, v33, v41

.LBB0_728:
	s_cmp_le_i32 s6, s17
	v_add_u32_e32 v64, s18, v120
	s_cselect_b64 s[20:21], -1, 0
	s_add_i32 s18, s6, 31
	s_cmp_ge_i32 s18, s19
	s_cselect_b64 s[38:39], -1, 0
	s_and_b64 s[20:21], s[20:21], s[38:39]
	v_add_u32_e32 v150, v64, v141
	s_andn2_b64 vcc, exec, s[20:21]
	v_add_u32_e32 v152, v64, v123
	s_cbranch_vccnz .LBB0_732
	ds_read_b128 v[64:67], v152
	ds_read_b128 v[154:157], v152 offset:32
	ds_read_b128 v[158:161], v152 offset:64
	ds_read_b128 v[162:165], v152 offset:96
	s_setprio 1
	s_waitcnt lgkmcnt(0)
	v_mfma_f32_32x32x16_bf16 v[64:79], v[64:67], v[80:83], 0
	v_mfma_f32_32x32x16_bf16 v[64:79], v[154:157], v[84:87], v[64:79]
	v_mfma_f32_32x32x16_bf16 v[64:79], v[158:161], v[88:91], v[64:79]
	v_mfma_f32_32x32x16_bf16 v[64:79], v[162:165], v[92:95], v[64:79]
	s_setprio 0
	s_nop 10
	s_sub_i32 m0, s17, 62
	s_cmp_le_i32 s6, m0
	s_cbranch_scc0 .Lwin0_masked
	s_add_i32 m0, s19, 31
	s_cmp_ge_i32 s6, m0
	s_cbranch_scc0 .Lwin0_masked
	v_mul_f32_e32 v162, 0x3e38aa3b, v64
	v_mul_f32_e32 v161, 0x3e38aa3b, v65
	v_mul_f32_e32 v160, 0x3e38aa3b, v66
	v_mul_f32_e32 v159, 0x3e38aa3b, v67
	v_mul_f32_e32 v158, 0x3e38aa3b, v68
	v_mul_f32_e32 v157, 0x3e38aa3b, v69
	v_mul_f32_e32 v156, 0x3e38aa3b, v70
	v_mul_f32_e32 v155, 0x3e38aa3b, v71
	v_max_f32_e32 v69, v156, v155
	v_mul_f32_e32 v154, 0x3e38aa3b, v72
	v_max3_f32 v69, v158, v157, v69
	v_mul_f32_e32 v72, 0x3e38aa3b, v73
	v_max_f32_e32 v73, v154, v72
	v_mul_f32_e32 v71, 0x3e38aa3b, v74
	v_mul_f32_e32 v70, 0x3e38aa3b, v75
	v_max_f32_e32 v74, v71, v70
	v_mul_f32_e32 v68, 0x3e38aa3b, v76
	v_mul_f32_e32 v67, 0x3e38aa3b, v77
	v_mul_f32_e32 v66, 0x3e38aa3b, v78
	v_max_f32_e32 v64, v160, v159
	v_max3_f32 v64, v162, v161, v64
	v_mul_f32_e32 v65, 0x3e38aa3b, v79
	v_max_f32_e32 v75, v66, v65
	v_max3_f32 v75, v68, v67, v75
	v_max3_f32 v73, v73, v74, v75
	v_max3_f32 v64, v64, v69, v73
	s_branch .Lwin0_join
.Lwin0_masked:
	v_mul_f32_e32 v64, 0x3e38aa3b, v64
	v_cmp_gt_u32_e32 vcc, s3, v147
	v_mul_f32_e32 v65, 0x3e38aa3b, v65
	s_nop 0
	v_cndmask_b32_e32 v162, v212, v64, vcc
	v_add_u32_e32 v64, s6, v148
	v_cmp_lt_u32_e32 vcc, s79, v64
	v_add_u32_e32 v64, -2, v147
	s_nop 0
	v_cndmask_b32_e32 v161, v212, v65, vcc
	v_mul_f32_e32 v65, 0x3e38aa3b, v66
	v_cmp_gt_u32_e32 vcc, s3, v64
	v_add_u32_e32 v64, -3, v147
	s_nop 0
	v_cndmask_b32_e32 v160, v212, v65, vcc
	v_mul_f32_e32 v65, 0x3e38aa3b, v67
	v_cmp_gt_u32_e32 vcc, s3, v64
	v_add_u32_e32 v64, -8, v147
	s_nop 0
	v_cndmask_b32_e32 v159, v212, v65, vcc
	v_mul_f32_e32 v65, 0x3e38aa3b, v68
	v_cmp_gt_u32_e32 vcc, s3, v64
	v_add_u32_e32 v64, -9, v147
	s_nop 0
	v_cndmask_b32_e32 v158, v212, v65, vcc
	v_mul_f32_e32 v65, 0x3e38aa3b, v69
	v_cmp_gt_u32_e32 vcc, s3, v64
	v_add_u32_e32 v64, -10, v147
	s_nop 0
	v_cndmask_b32_e32 v157, v212, v65, vcc
	v_mul_f32_e32 v65, 0x3e38aa3b, v70
	v_cmp_gt_u32_e32 vcc, s3, v64
	v_add_u32_e32 v64, -11, v147
	s_nop 0
	v_cndmask_b32_e32 v156, v212, v65, vcc
	v_mul_f32_e32 v65, 0x3e38aa3b, v71
	v_cmp_gt_u32_e32 vcc, s3, v64
	v_add_u32_e32 v64, -16, v147
	s_nop 0
	v_cndmask_b32_e32 v155, v212, v65, vcc
	v_mul_f32_e32 v65, 0x3e38aa3b, v72
	v_cmp_gt_u32_e32 vcc, s3, v64
	v_subrev_u32_e32 v64, 17, v147
	v_max_f32_e32 v69, v156, v155
	v_cndmask_b32_e32 v154, v212, v65, vcc
	v_mul_f32_e32 v65, 0x3e38aa3b, v73
	v_cmp_gt_u32_e32 vcc, s3, v64
	v_subrev_u32_e32 v64, 18, v147
	v_max3_f32 v69, v158, v157, v69
	v_cndmask_b32_e32 v72, v212, v65, vcc
	v_mul_f32_e32 v65, 0x3e38aa3b, v74
	v_cmp_gt_u32_e32 vcc, s3, v64
	v_subrev_u32_e32 v64, 19, v147
	v_max_f32_e32 v73, v154, v72
	v_cndmask_b32_e32 v71, v212, v65, vcc
	v_mul_f32_e32 v65, 0x3e38aa3b, v75
	v_cmp_gt_u32_e32 vcc, s3, v64
	v_subrev_u32_e32 v64, 24, v147
	s_nop 0
	v_cndmask_b32_e32 v70, v212, v65, vcc
	v_mul_f32_e32 v65, 0x3e38aa3b, v76
	v_cmp_gt_u32_e32 vcc, s3, v64
	v_subrev_u32_e32 v64, 25, v147
	v_max_f32_e32 v74, v71, v70
	v_cndmask_b32_e32 v68, v212, v65, vcc
	v_mul_f32_e32 v65, 0x3e38aa3b, v77
	v_cmp_gt_u32_e32 vcc, s3, v64
	v_subrev_u32_e32 v64, 26, v147
	s_nop 0
	v_cndmask_b32_e32 v67, v212, v65, vcc
	v_mul_f32_e32 v65, 0x3e38aa3b, v78
	v_cmp_gt_u32_e32 vcc, s3, v64
	v_subrev_u32_e32 v64, 27, v147
	s_nop 0
	v_cndmask_b32_e32 v66, v212, v65, vcc
	v_mul_f32_e32 v65, 0x3e38aa3b, v79
	v_cmp_gt_u32_e32 vcc, s3, v64
	v_max_f32_e32 v64, v160, v159
	v_max3_f32 v64, v162, v161, v64
	v_cndmask_b32_e32 v65, v212, v65, vcc
	v_max_f32_e32 v75, v66, v65
	v_max3_f32 v75, v68, v67, v75
	v_max3_f32 v73, v73, v74, v75
	v_max3_f32 v64, v64, v69, v73
.Lwin0_join:
	ds_bpermute_b32 v69, v121, v64
	s_waitcnt lgkmcnt(0)
	v_max3_f32 v153, v151, v64, v69
	v_cmp_neq_f32_e32 vcc, s29, v153
	s_nop 1
	v_cndmask_b32_e32 v69, 0, v153, vcc
	v_sub_f32_e32 v64, v151, v69
	v_exp_f32_e32 v64, v64
	s_nop 0
	v_cmp_eq_f32_e32 vcc, 1.0, v64
	s_cmp_eq_u64 vcc, exec
	s_cbranch_scc1 .LBB0_731
	v_pk_mul_f32 v[46:47], v[46:47], v[64:65] op_sel_hi:[1,0]
	v_pk_mul_f32 v[44:45], v[44:45], v[64:65] op_sel_hi:[1,0]
	v_pk_mul_f32 v[42:43], v[42:43], v[64:65] op_sel_hi:[1,0]
	v_pk_mul_f32 v[40:41], v[40:41], v[64:65] op_sel_hi:[1,0]
	v_pk_mul_f32 v[38:39], v[38:39], v[64:65] op_sel_hi:[1,0]
	v_pk_mul_f32 v[36:37], v[36:37], v[64:65] op_sel_hi:[1,0]
	v_pk_mul_f32 v[34:35], v[34:35], v[64:65] op_sel_hi:[1,0]
	v_pk_mul_f32 v[32:33], v[32:33], v[64:65] op_sel_hi:[1,0]
	v_pk_mul_f32 v[62:63], v[62:63], v[64:65] op_sel_hi:[1,0]
	v_pk_mul_f32 v[60:61], v[60:61], v[64:65] op_sel_hi:[1,0]
	v_pk_mul_f32 v[58:59], v[58:59], v[64:65] op_sel_hi:[1,0]
	v_pk_mul_f32 v[56:57], v[56:57], v[64:65] op_sel_hi:[1,0]
	v_pk_mul_f32 v[54:55], v[54:55], v[64:65] op_sel_hi:[1,0]
	v_pk_mul_f32 v[52:53], v[52:53], v[64:65] op_sel_hi:[1,0]
	v_pk_mul_f32 v[50:51], v[50:51], v[64:65] op_sel_hi:[1,0]
	v_pk_mul_f32 v[48:49], v[48:49], v[64:65] op_sel_hi:[1,0]

.LBB0_733:
	s_add_i32 s18, s6, 32
	s_cmp_le_i32 s18, s17
	s_cselect_b64 s[20:21], -1, 0
	s_add_i32 s18, s6, 63
	s_cmp_ge_i32 s18, s19
	s_cselect_b64 s[38:39], -1, 0
	s_and_b64 s[20:21], s[20:21], s[38:39]
	s_andn2_b64 vcc, exec, s[20:21]
	s_cbranch_vccnz .LBB0_724
	ds_read_b128 v[64:67], v152 offset:4608
	ds_read_b128 v[154:157], v152 offset:4640
	ds_read_b128 v[158:161], v152 offset:4672
	ds_read_b128 v[162:165], v152 offset:4704
	s_setprio 1
	s_waitcnt lgkmcnt(0)
	v_mfma_f32_32x32x16_bf16 v[64:79], v[64:67], v[80:83], 0
	v_mfma_f32_32x32x16_bf16 v[64:79], v[154:157], v[84:87], v[64:79]
	v_mfma_f32_32x32x16_bf16 v[64:79], v[158:161], v[88:91], v[64:79]
	v_mfma_f32_32x32x16_bf16 v[64:79], v[162:165], v[92:95], v[64:79]
	s_setprio 0
	v_subrev_u32_e32 v151, 32, v147
	s_nop 9
	s_sub_i32 m0, s17, 94
	s_cmp_le_i32 s6, m0
	s_cbranch_scc0 .Lwin1_masked
	s_add_i32 m0, s19, -1
	s_cmp_ge_i32 s6, m0
	s_cbranch_scc0 .Lwin1_masked
	v_mul_f32_e32 v161, 0x3e38aa3b, v64
	v_mul_f32_e32 v160, 0x3e38aa3b, v65
	v_mul_f32_e32 v159, 0x3e38aa3b, v66
	v_mul_f32_e32 v158, 0x3e38aa3b, v67
	v_mul_f32_e32 v157, 0x3e38aa3b, v68
	v_mul_f32_e32 v156, 0x3e38aa3b, v69
	v_mul_f32_e32 v155, 0x3e38aa3b, v70
	v_mul_f32_e32 v154, 0x3e38aa3b, v71
	v_max_f32_e32 v69, v155, v154
	v_mul_f32_e32 v152, 0x3e38aa3b, v72
	v_max3_f32 v69, v157, v156, v69
	v_mul_f32_e32 v72, 0x3e38aa3b, v73
	v_max_f32_e32 v73, v152, v72
	v_mul_f32_e32 v71, 0x3e38aa3b, v74
	v_mul_f32_e32 v70, 0x3e38aa3b, v75
	v_max_f32_e32 v74, v71, v70
	v_mul_f32_e32 v68, 0x3e38aa3b, v76
	v_mul_f32_e32 v67, 0x3e38aa3b, v77
	v_mul_f32_e32 v66, 0x3e38aa3b, v78
	v_max_f32_e32 v64, v159, v158
	v_max3_f32 v64, v161, v160, v64
	v_mul_f32_e32 v65, 0x3e38aa3b, v79
	v_max_f32_e32 v75, v66, v65
	v_max3_f32 v75, v68, v67, v75
	v_max3_f32 v73, v73, v74, v75
	v_max3_f32 v64, v64, v69, v73
	s_branch .Lwin1_join
.Lwin1_masked:
	v_mul_f32_e32 v64, 0x3e38aa3b, v64
	v_cmp_gt_u32_e32 vcc, s3, v151
	v_mul_f32_e32 v65, 0x3e38aa3b, v65
	s_nop 0
	v_cndmask_b32_e32 v161, v212, v64, vcc
	v_add3_u32 v64, v113, s6, 32
	v_cmp_lt_u32_e32 vcc, s79, v64
	v_subrev_u32_e32 v64, 34, v147
	s_nop 0
	v_cndmask_b32_e32 v160, v212, v65, vcc
	v_mul_f32_e32 v65, 0x3e38aa3b, v66
	v_cmp_gt_u32_e32 vcc, s3, v64
	v_subrev_u32_e32 v64, 35, v147
	s_nop 0
	v_cndmask_b32_e32 v159, v212, v65, vcc
	v_mul_f32_e32 v65, 0x3e38aa3b, v67
	v_cmp_gt_u32_e32 vcc, s3, v64
	v_subrev_u32_e32 v64, 40, v147
	s_nop 0
	v_cndmask_b32_e32 v158, v212, v65, vcc
	v_mul_f32_e32 v65, 0x3e38aa3b, v68
	v_cmp_gt_u32_e32 vcc, s3, v64
	v_subrev_u32_e32 v64, 41, v147
	s_nop 0
	v_cndmask_b32_e32 v157, v212, v65, vcc
	v_mul_f32_e32 v65, 0x3e38aa3b, v69
	v_cmp_gt_u32_e32 vcc, s3, v64
	v_subrev_u32_e32 v64, 42, v147
	s_nop 0
	v_cndmask_b32_e32 v156, v212, v65, vcc
	v_mul_f32_e32 v65, 0x3e38aa3b, v70
	v_cmp_gt_u32_e32 vcc, s3, v64
	v_subrev_u32_e32 v64, 43, v147
	s_nop 0
	v_cndmask_b32_e32 v155, v212, v65, vcc
	v_mul_f32_e32 v65, 0x3e38aa3b, v71
	v_cmp_gt_u32_e32 vcc, s3, v64
	v_subrev_u32_e32 v64, 48, v147
	s_nop 0
	v_cndmask_b32_e32 v154, v212, v65, vcc
	v_mul_f32_e32 v65, 0x3e38aa3b, v72
	v_cmp_gt_u32_e32 vcc, s3, v64
	v_subrev_u32_e32 v64, 49, v147
	v_max_f32_e32 v69, v155, v154
	v_cndmask_b32_e32 v152, v212, v65, vcc
	v_mul_f32_e32 v65, 0x3e38aa3b, v73
	v_cmp_gt_u32_e32 vcc, s3, v64
	v_subrev_u32_e32 v64, 50, v147
	v_max3_f32 v69, v157, v156, v69
	v_cndmask_b32_e32 v72, v212, v65, vcc
	v_mul_f32_e32 v65, 0x3e38aa3b, v74
	v_cmp_gt_u32_e32 vcc, s3, v64
	v_subrev_u32_e32 v64, 51, v147
	v_max_f32_e32 v73, v152, v72
	v_cndmask_b32_e32 v71, v212, v65, vcc
	v_mul_f32_e32 v65, 0x3e38aa3b, v75
	v_cmp_gt_u32_e32 vcc, s3, v64
	v_subrev_u32_e32 v64, 56, v147
	s_nop 0
	v_cndmask_b32_e32 v70, v212, v65, vcc
	v_mul_f32_e32 v65, 0x3e38aa3b, v76
	v_cmp_gt_u32_e32 vcc, s3, v64
	v_subrev_u32_e32 v64, 57, v147
	v_max_f32_e32 v74, v71, v70
	v_cndmask_b32_e32 v68, v212, v65, vcc
	v_mul_f32_e32 v65, 0x3e38aa3b, v77
	v_cmp_gt_u32_e32 vcc, s3, v64
	v_subrev_u32_e32 v64, 58, v147
	s_nop 0
	v_cndmask_b32_e32 v67, v212, v65, vcc
	v_mul_f32_e32 v65, 0x3e38aa3b, v78
	v_cmp_gt_u32_e32 vcc, s3, v64
	v_subrev_u32_e32 v64, 59, v147
	s_nop 0
	v_cndmask_b32_e32 v66, v212, v65, vcc
	v_mul_f32_e32 v65, 0x3e38aa3b, v79
	v_cmp_gt_u32_e32 vcc, s3, v64
	v_max_f32_e32 v64, v159, v158
	v_max3_f32 v64, v161, v160, v64
	v_cndmask_b32_e32 v65, v212, v65, vcc
	v_max_f32_e32 v75, v66, v65
	v_max3_f32 v75, v68, v67, v75
	v_max3_f32 v73, v73, v74, v75
	v_max3_f32 v64, v64, v69, v73
.Lwin1_join:
	ds_bpermute_b32 v69, v121, v64
	s_waitcnt lgkmcnt(0)
	v_max3_f32 v151, v153, v64, v69
	v_cmp_neq_f32_e32 vcc, s29, v151
	s_nop 1
	v_cndmask_b32_e32 v69, 0, v151, vcc
	v_sub_f32_e32 v64, v153, v69
	v_exp_f32_e32 v64, v64
	s_nop 0
	v_cmp_eq_f32_e32 vcc, 1.0, v64
	s_cmp_eq_u64 vcc, exec
	s_cbranch_scc1 .LBB0_736
	v_pk_mul_f32 v[46:47], v[46:47], v[64:65] op_sel_hi:[1,0]
	v_pk_mul_f32 v[44:45], v[44:45], v[64:65] op_sel_hi:[1,0]
	v_pk_mul_f32 v[42:43], v[42:43], v[64:65] op_sel_hi:[1,0]
	v_pk_mul_f32 v[40:41], v[40:41], v[64:65] op_sel_hi:[1,0]
	v_pk_mul_f32 v[38:39], v[38:39], v[64:65] op_sel_hi:[1,0]
	v_pk_mul_f32 v[36:37], v[36:37], v[64:65] op_sel_hi:[1,0]
	v_pk_mul_f32 v[34:35], v[34:35], v[64:65] op_sel_hi:[1,0]
	v_pk_mul_f32 v[32:33], v[32:33], v[64:65] op_sel_hi:[1,0]
	v_pk_mul_f32 v[62:63], v[62:63], v[64:65] op_sel_hi:[1,0]
	v_pk_mul_f32 v[60:61], v[60:61], v[64:65] op_sel_hi:[1,0]
	v_pk_mul_f32 v[58:59], v[58:59], v[64:65] op_sel_hi:[1,0]
	v_pk_mul_f32 v[56:57], v[56:57], v[64:65] op_sel_hi:[1,0]
	v_pk_mul_f32 v[54:55], v[54:55], v[64:65] op_sel_hi:[1,0]
	v_pk_mul_f32 v[52:53], v[52:53], v[64:65] op_sel_hi:[1,0]
	v_pk_mul_f32 v[50:51], v[50:51], v[64:65] op_sel_hi:[1,0]
	v_pk_mul_f32 v[48:49], v[48:49], v[64:65] op_sel_hi:[1,0]
